# seam barriers: XCD leader no longer waits for its fire-and-forget release atomics before the closing barrier
# baseline (speedup 1.0000x reference)
.LBB0_164:
	s_or_b64 exec, exec, s[12:13]
	s_mov_b64 s[12:13], exec
	v_mbcnt_lo_u32_b32 v0, s12, 0
	v_mbcnt_hi_u32_b32 v0, s13, v0
	v_cmp_eq_u32_e32 vcc, 0, v0
	s_nop 0
	s_nop 0
	s_and_saveexec_b64 s[14:15], vcc
	s_cbranch_execz .LBB0_166
	s_bcnt1_i32_b64 s12, s[12:13]
	v_mov_b32_e32 v0, 0x2000
	v_mov_b32_e32 v1, s12
	s_nop 0
.LBB0_166:
	s_or_b64 exec, exec, s[14:15]
	s_nop 0

.LBB0_567:
	s_or_b64 exec, exec, s[10:11]
	s_mov_b64 s[10:11], exec
	v_mbcnt_lo_u32_b32 v0, s10, 0
	v_mbcnt_hi_u32_b32 v0, s11, v0
	v_cmp_eq_u32_e32 vcc, 0, v0
	s_nop 0
	s_nop 0
	s_and_saveexec_b64 s[12:13], vcc
	s_cbranch_execz .LBB0_569
	s_bcnt1_i32_b64 s10, s[10:11]
	v_mov_b32_e32 v0, 0x2000
	v_mov_b32_e32 v1, s10
	s_nop 0
.LBB0_569:
	s_or_b64 exec, exec, s[12:13]
	s_nop 0
